# v35: v34 with the P3 classes swapped (odd workgroups tail first, even workgroups tail after their GEMM tiles)
# baseline (speedup 1.0000x reference)
; #define LAS __attribute__((address_space(3)))
; #define PHASE_IDS() const int tid = fresh_tid(), lane = tid & 63, wave = __builtin_amdgcn_readfirstlane(tid >> 6), gw = bx * NWAVES + wave; (void)lane; (void)gw
; __global__ void __launch_bounds__(NWAVES * 64, 2) fwd_megakernel(Args args) {
;     ...
;         if (G == 256) {
;             PHASE_IDS();
;             const int tm = bx >> 4, tn = bx & 15, row0 = MP + 32 * tm, col0 = 64 * tn, br = wave >> 2, kw = (wave & 3) * 128;
;             LAS float* parts = (LAS float*)lds;
;             tail_partial<4>(U + (size_t)row0 * LDU + (br ? C_QB : C_QA) + kw, LDU, WO_t + br * 512 + kw, DM, col0, parts + wave * 2048, lane);
.LBB0_710:
	s_or_b64 exec, exec, s[0:1]
	v_readlane_b32 s2, v254, 19
	s_lshl_b32 s92, s94, 1
	v_readlane_b32 s3, v254, 20
	s_andn2_b32 s92, s92, 31
	s_lshl_b32 s23, s94, 6
	s_waitcnt lgkmcnt(0)
	v_cndmask_b32_e64 v1, 0, 1, s[2:3]
	s_mov_b32 s0, 0x8000
	s_add_i32 s84, s92, 0x8000
	s_and_b32 s22, s23, 0x3c0
	v_cmp_ne_u32_e64 s[38:39], 1, v1
	s_andn2_b64 vcc, exec, s[2:3]
	s_movk_i32 s85, 0x82
	s_barrier
	s_cbranch_vccnz .LBB0_712
	s_mov_b32 s40, 0
	s_bitcmp1_b32 s94, 0
	s_cbranch_scc1 .Lp3_tail
	s_movk_i32 s85, 0x80
	s_branch .LBB0_712

; #define LAS __attribute__((address_space(3)))
; #define PG8_WAIT_V(n) asm volatile("s_waitcnt vmcnt(" #n ")" ::: "memory")
; #define PG8_BAR __builtin_amdgcn_s_barrier()
; template <class Epi, int AC0, int BC0, int NT0, int AC1, int BC1, int NT1>
; __device__ __forceinline__ void gemm_phase(LAS unsigned char* lds, const Gemm g, const StaticOrder& S, const Epi& E, int tid) {
;     ...
;     PG8_WAIT_V(0);
;     PG8_BAR;
; __global__ void __launch_bounds__(NWAVES * 64, 2) fwd_megakernel(Args args) {
;     ...
;             const int tm = bx >> 4, tn = bx & 15, row0 = MP + 32 * tm, col0 = 64 * tn, br = wave >> 2, kw = (wave & 3) * 128;
;             LAS float* parts = (LAS float*)lds;
;             tail_partial<4>(U + (size_t)row0 * LDU + (br ? C_QB : C_QA) + kw, LDU, WO_t + br * 512 + kw, DM, col0, parts + wave * 2048, lane);
.LBB0_829:
	s_waitcnt vmcnt(0)
	v_readlane_b32 s94, v254, 10
	v_readlane_b32 s20, v254, 4
	v_readlane_b32 s95, v254, 11
	v_readlane_b32 s93, v254, 12
	v_readlane_b32 s21, v254, 5
	s_bitcmp1_b32 s94, 0
	s_cbranch_scc1 .Lp3_ret
	s_barrier
	s_mov_b32 s40, 1
	s_mov_b32 s0, 0x8000
	s_add_u32 s8, s62, 0xd00000
	s_addc_u32 s9, s63, 0
	s_branch .Lp3_tail
